# speedup vs baseline: 1.0060x; 1.0060x over previous
; __device__ __forceinline__ int v_st(int k, int c) { const int kk = (k & ~0xC) | ((k & 4) << 1) | ((k & 8) >> 1); return ((kk >> 3) * 4 + (c >> 5)) * 512 + ((kk & 7) * 32 + (c & 31)) * 2; }
; #define SLOADX(S, k0) do { const bf16_t* Vt_ = Vh + (size_t)(k0) * ldk; const bf16_t* Kt_ = Kh + (size_t)(k0) * ldk; \
;     S.vs0 = *(const bf16x8*)(Vt_ + voff0); S.vs1 = *(const bf16x8*)(Vt_ + voff1); \
;     S.ks0 = *(const bf16x8*)(Kt_ + voff0); S.ks1 = *(const bf16x8*)(Kt_ + voff1); \
;     if (MODE == 0) S.kr = *(const bf16x8*)(KRh + (size_t)(k0) * 64 + kroff); } while (0)
; __device__ __forceinline__ void rot8(bf16x8& a, bf16x8& b, const f32x2* t) {
;     float x1[8], x2[8], y1[8], y2[8]; unpack8(a, x1); unpack8(b, x2);
; #pragma unroll
;     for (int j = 0; j < 8; ++j) { const f32x2 cs = t[j]; y1[j] = x1[j] * cs.x - x2[j] * cs.y; y2[j] = x2[j] * cs.x + x1[j] * cs.y; }
;     a = pack8(y1); b = pack8(y2);
; }
; template <int MODE> ...
;     ...
;     const int sr = tid >> 4, sc = (tid & 15) * 8, vst0 = v_st(sr, sc), vst1 = v_st(32 + sr, sc);
;     const int krr = tid >> 3, krc = (tid & 7) * 8;
;     const unsigned voff0 = (unsigned)(sr * ldk + sc), voff1 = voff0 + 32u * (unsigned)ldk, kroff = (unsigned)(krr * 64 + krc);
;     struct Stg { bf16x8 vs0, vs1, ks0, ks1, kr; };
;     Stg sg, sh;
;     ...
;     SLOADX(sg, 0); SLOADX(sh, 64);
;     bf16x8 qr[NQ];
;     const bf16_t* Qw = Qb + (unsigned)((wid * 32 + r32) * ldq + hi * 8);
; #pragma unroll
;     for (int d0 = 0; d0 < NQ; ++d0) qr[d0] = *(const bf16x8*)(Qw + d0 * 16);
;     const int qpos = qpos0 + wid * 32 + r32;
;     if (MODE == 0) {
; #pragma unroll
;         for (int dd = 0; dd < 2; ++dd) rot8(qr[(MODE == 0) ? 8 + dd : 0], qr[(MODE == 0) ? 10 + dd : 1], TA + (unsigned)(qpos * 32 + dd * 16 + hi * 8));
;     } else if (MODE == 1) {
;         rot8(qr[0], qr[1], TB + (unsigned)(qpos * 16 + hi * 8));
.LBB0_185:
	s_lshl_b32 s33, s6, 8
	v_mov_b32_e32 v0, 0x80
	v_sub_u32_e64 v0, s33, v0 clamp
	s_add_i32 s5, s33, 0x180
	v_readfirstlane_b32 s83, v0
	s_min_u32 s9, s5, s4
	s_add_i32 s4, s83, s8
	s_mul_i32 s94, s4, 0x1400
	s_lshl_b64 s[4:5], s[94:95], 1
	s_add_u32 s4, s58, s4
	s_addc_u32 s5, s59, s5
	s_lshl_b32 s6, s0, 6
	s_and_b32 s6, s6, 0xffffff00
	s_add_u32 s6, s4, s6
	s_addc_u32 s7, s5, 0
	s_add_u32 s72, s6, 0x1000
	s_addc_u32 s73, s7, 0
	s_add_i32 s4, s33, s8
	s_mul_i32 s94, s4, 0x1400
	s_lshl_b64 s[4:5], s[94:95], 1
	s_add_u32 s67, s58, s4
	s_addc_u32 s82, s59, s5
	s_lshl_b32 s4, s0, 8
	s_add_u32 s4, s67, s4
	s_addc_u32 s5, s82, 0
	s_add_i32 s94, s0, s64
	s_sub_i32 s45, s9, s83
	s_lshl_b64 s[8:9], s[94:95], 2
	v_readlane_b32 s10, v254, 60
	v_readlane_b32 s11, v254, 61
	s_add_u32 s8, s10, s8
	s_addc_u32 s9, s11, s9
	v_mov_b32_e32 v1, v201
	global_load_dword v176, v181, s[8:9]
	v_mov_b32_e32 v179, v181
	v_ashrrev_i32_e32 v42, 4, v1
	v_and_b32_e32 v3, 0xfffff0, v42
	v_lshlrev_b32_e32 v4, 1, v42
	v_lshlrev_b32_e32 v2, 3, v1
	v_and_or_b32 v3, v4, 8, v3
	v_and_b32_e32 v182, 0x78, v2
	v_lshrrev_b32_e32 v3, 1, v3
	v_bfe_u32 v2, v2, 5, 2
	v_or_b32_e32 v3, v3, v2
	v_lshrrev_b32_e32 v4, 1, v42
	v_lshlrev_b32_e32 v28, 9, v3
	v_and_b32_e32 v3, 3, v42
	v_and_or_b32 v3, v4, 4, v3
	v_add_u32_e32 v44, 32, v42
	s_waitcnt lgkmcnt(0)
	v_lshlrev_b32_e32 v45, 6, v3
	v_and_b32_e32 v3, 0xfffff0, v44
	v_lshlrev_b32_e32 v4, 1, v44
	v_and_or_b32 v3, v4, 8, v3
	v_readfirstlane_b32 s44, v1
	v_lshrrev_b32_e32 v3, 1, v3
	s_ashr_i32 s66, s44, 6
	v_or_b32_e32 v2, v3, v2
	v_lshlrev_b32_e32 v46, 9, v2
	v_mul_lo_u32 v2, v42, s74
	s_add_u32 s8, s6, 0xa1400
	v_or_b32_e32 v180, v2, v182
	s_addc_u32 s9, s7, 0
	v_add_u32_e32 v178, 0x28000, v180
	s_add_u32 s6, s6, 0xa1000
	v_and_b32_e32 v183, 31, v1
	v_lshlrev_b64 v[48:49], 1, v[180:181]
	v_lshlrev_b64 v[50:51], 1, v[178:179]
	s_addc_u32 s7, s7, 0
	s_lshl_b32 s86, s66, 5
	v_bfe_u32 v184, v1, 5, 1
	v_lshl_add_u64 v[2:3], s[72:73], 0, v[48:49]
	v_lshl_add_u64 v[4:5], s[72:73], 0, v[50:51]
	v_or_b32_e32 v18, s86, v183
	v_mov_b32 v0, 0
	global_load_dwordx4 v[96:99], v[2:3], off offset:1024
	global_load_dwordx4 v[100:103], v[4:5], off offset:1024
	global_load_dwordx4 v[104:107], v[2:3], off
	global_load_dwordx4 v[108:111], v[4:5], off
	v_lshl_add_u64 v[2:3], s[8:9], 0, v[48:49]
	v_lshl_add_u64 v[6:7], s[8:9], 0, v[50:51]
	v_mul_lo_u32 v18, v18, s74
	v_lshlrev_b32_e32 v29, 3, v184
	global_load_dwordx4 v[2:5], v[2:3], off
	v_lshl_add_u64 v[10:11], s[6:7], 0, v[50:51]
	global_load_dwordx4 v[14:17], v[6:7], off
	v_lshl_add_u64 v[6:7], s[6:7], 0, v[48:49]
	v_or_b32_e32 v18, v18, v29
	v_mov_b32_e32 v19, v181
	s_add_i32 s6, s86, s33
	v_lshl_add_u64 v[26:27], v[18:19], 1, s[4:5]
	v_or_b32_e32 v54, s6, v183
	v_lshlrev_b32_e32 v43, 1, v182
	global_load_dwordx4 v[6:9], v[6:7], off
	v_and_b32_e32 v47, 48, v43
	global_load_dwordx4 v[10:13], v[10:11], off
	s_nop 0
	global_load_dwordx4 v[18:21], v[26:27], off
	global_load_dwordx4 v[22:25], v[26:27], off offset:32
	global_load_dwordx4 v[112:115], v[26:27], off offset:64
	global_load_dwordx4 v[116:119], v[26:27], off offset:96
	global_load_dwordx4 v[120:123], v[26:27], off offset:128
	global_load_dwordx4 v[124:127], v[26:27], off offset:160
	global_load_dwordx4 v[128:131], v[26:27], off offset:192
	global_load_dwordx4 v[132:135], v[26:27], off offset:224
	v_lshl_or_b32 v26, v54, 4, v29
	v_mov_b32_e32 v27, v181
	v_lshl_add_u64 v[38:39], v[26:27], 3, s[88:89]
	v_or3_b32 v185, v28, v45, v47
	global_load_dwordx4 v[26:29], v[38:39], off offset:48
	global_load_dwordx4 v[30:33], v[38:39], off offset:32
	global_load_dwordx4 v[34:37], v[38:39], off offset:16
	s_nop 0
	global_load_dwordx4 v[38:41], v[38:39], off
	s_lshl_b32 s4, s66, 2
	s_add_i32 s4, s4, 0
	s_add_i32 s4, s4, 0x22880
	v_or3_b32 v203, v46, v45, v47
	s_add_i32 s5, 0, 0x14000
	s_waitcnt vmcnt(11)
	v_lshlrev_b32_e32 v53, 16, v18
	s_waitcnt vmcnt(10)
	v_lshlrev_b32_e32 v52, 16, v22
	s_waitcnt vmcnt(0)
	v_pk_mul_f32 v[56:57], v[38:39], v[52:53] op_sel:[0,1] op_sel_hi:[1,0]
	v_pk_mul_f32 v[38:39], v[38:39], v[52:53]
	v_sub_f32_e32 v55, v56, v57
	v_add_f32_e32 v56, v39, v38
	v_and_b32_e32 v39, 0xffff0000, v18
	v_and_b32_e32 v38, 0xffff0000, v22
	v_pk_mul_f32 v[52:53], v[40:41], v[38:39] op_sel:[0,1] op_sel_hi:[1,0]
	v_pk_mul_f32 v[38:39], v[40:41], v[38:39]
	v_sub_f32_e32 v52, v52, v53
	v_add_f32_e32 v53, v39, v38
	v_lshlrev_b32_e32 v39, 16, v19
	v_and_b32_e32 v19, 0xffff0000, v19
	v_and_b32_e32 v18, 0xffff0000, v23
	v_lshlrev_b32_e32 v38, 16, v23
	v_pk_mul_f32 v[22:23], v[36:37], v[18:19] op_sel:[0,1] op_sel_hi:[1,0]
	v_pk_mul_f32 v[18:19], v[36:37], v[18:19]
	v_pk_mul_f32 v[40:41], v[34:35], v[38:39] op_sel:[0,1] op_sel_hi:[1,0]
	v_pk_mul_f32 v[34:35], v[34:35], v[38:39]
	v_add_f32_e32 v36, v18, v19
	v_lshlrev_b32_e32 v19, 16, v20
	v_lshlrev_b32_e32 v18, 16, v24
	v_add_f32_e32 v34, v34, v35
	v_sub_f32_e32 v35, v22, v23
	v_pk_mul_f32 v[22:23], v[30:31], v[18:19] op_sel:[0,1] op_sel_hi:[1,0]
	v_pk_mul_f32 v[18:19], v[30:31], v[18:19]
	v_sub_f32_e32 v37, v22, v23
	v_add_f32_e32 v30, v18, v19
	v_and_b32_e32 v19, 0xffff0000, v20
	v_and_b32_e32 v18, 0xffff0000, v24
	v_pk_mul_f32 v[22:23], v[32:33], v[18:19] op_sel:[0,1] op_sel_hi:[1,0]
	v_pk_mul_f32 v[18:19], v[32:33], v[18:19]
	v_sub_f32_e32 v24, v22, v23
	v_add_f32_e32 v31, v18, v19
	v_lshlrev_b32_e32 v19, 16, v21
	v_lshlrev_b32_e32 v18, 16, v25
	v_pk_mul_f32 v[22:23], v[26:27], v[18:19] op_sel:[0,1] op_sel_hi:[1,0]
	v_pk_mul_f32 v[18:19], v[26:27], v[18:19]
	v_sub_f32_e32 v22, v22, v23
	v_add_f32_e32 v23, v18, v19
	v_and_b32_e32 v19, 0xffff0000, v21
	v_and_b32_e32 v18, 0xffff0000, v25
	v_pk_mul_f32 v[20:21], v[28:29], v[18:19] op_sel:[0,1] op_sel_hi:[1,0]
	v_pk_mul_f32 v[18:19], v[28:29], v[18:19]
	v_sub_f32_e32 v40, v40, v41
	v_add_f32_e32 v18, v18, v19
	v_sub_f32_e32 v20, v20, v21
	v_cvt_pk_bf16_f32 v136, v55, v52
	v_cvt_pk_bf16_f32 v137, v40, v35
	v_cvt_pk_bf16_f32 v138, v37, v24
	v_cvt_pk_bf16_f32 v139, v22, v20
	v_cvt_pk_bf16_f32 v140, v56, v53
	v_cvt_pk_bf16_f32 v141, v34, v36
	v_cvt_pk_bf16_f32 v142, v30, v31
	v_cvt_pk_bf16_f32 v143, v23, v18
	v_mov_b32_e32 v18, s4
	ds_read_b32 v18, v18
	v_and_b32_e32 v19, 0x70, v1
	s_add_i32 s4, 0, 0x10000
	v_add_u32_e32 v52, 0, v185
	v_add_u32_e32 v53, 0, v203
	s_waitcnt lgkmcnt(0)
	v_readfirstlane_b32 s87, v18
	v_lshlrev_b32_e32 v18, 8, v42
	v_bitop3_b32 v204, v43, v18, v19 bitop3:0xde
	v_add_u32_e32 v18, s4, v204
	s_waitcnt vmcnt(0)
	ds_write_b128 v52, v[96:99]
	ds_write_b128 v53, v[100:103]
	ds_write_b128 v18, v[104:107]
	v_lshlrev_b32_e32 v18, 8, v44
	v_bitop3_b32 v205, v43, v18, v19 bitop3:0xde
	v_add_u32_e32 v18, s4, v205
	ds_write_b128 v18, v[108:111]
	ds_write_b128 v52, v[2:5] offset:16384
	ds_write_b128 v53, v[14:17] offset:16384
	v_add_u32_e32 v2, s5, v204
	s_cmpk_gt_i32 s45, 0xbf
	ds_write_b128 v2, v[6:9]
	v_add_u32_e32 v2, s5, v205
	s_cselect_b64 s[42:43], -1, 0
	s_cmpk_lt_i32 s45, 0xc0
	ds_write_b128 v2, v[10:13]
	s_cbranch_scc1 .LBB0_187
; #define SLOAD(k0) SLOADX(sg, k0)
; template <int MODE> ...
;     ...
;     asm volatile("s_waitcnt vmcnt(0)" ::: "memory"); SWRITEX(sg, 0, 0); SWRITEX(sh, 1, 1); if (2 < NT) SLOAD(128);
	s_add_u32 s8, s72, 0x140000
	s_addc_u32 s9, s73, 0
	v_lshl_add_u64 v[2:3], s[8:9], 0, v[50:51]
	v_lshl_add_u64 v[4:5], s[8:9], 0, v[48:49]
	s_add_u32 s8, s72, 0x140400
	s_addc_u32 s9, s73, 0
	v_lshl_add_u64 v[8:9], s[8:9], 0, v[48:49]
	v_lshl_add_u64 v[6:7], s[8:9], 0, v[50:51]
	global_load_dwordx4 v[96:99], v[8:9], off
	global_load_dwordx4 v[100:103], v[6:7], off
	global_load_dwordx4 v[104:107], v[4:5], off
	global_load_dwordx4 v[108:111], v[2:3], off

; #define LAS __attribute__((address_space(3)))
; __device__ __forceinline__ int v_st(int k, int c) { const int kk = (k & ~0xC) | ((k & 4) << 1) | ((k & 8) >> 1); return ((kk >> 3) * 4 + (c >> 5)) * 512 + ((kk & 7) * 32 + (c & 31)) * 2; }
; #define SLOADX(S, k0) do { const bf16_t* Vt_ = Vh + (size_t)(k0) * ldk; const bf16_t* Kt_ = Kh + (size_t)(k0) * ldk; \
;     S.vs0 = *(const bf16x8*)(Vt_ + voff0); S.vs1 = *(const bf16x8*)(Vt_ + voff1); \
;     S.ks0 = *(const bf16x8*)(Kt_ + voff0); S.ks1 = *(const bf16x8*)(Kt_ + voff1); \
;     if (MODE == 0) S.kr = *(const bf16x8*)(KRh + (size_t)(k0) * 64 + kroff); } while (0)
; template <int MODE> ...
;     ...
;     const int sr = tid >> 4, sc = (tid & 15) * 8, vst0 = v_st(sr, sc), vst1 = v_st(32 + sr, sc);
;     const int krr = tid >> 3, krc = (tid & 7) * 8;
;     const unsigned voff0 = (unsigned)(sr * ldk + sc), voff1 = voff0 + 32u * (unsigned)ldk, kroff = (unsigned)(krr * 64 + krc);
;     struct Stg { bf16x8 vs0, vs1, ks0, ks1, kr; };
;     Stg sg, sh;
;     ...
;     SLOADX(sg, 0); SLOADX(sh, 64);
;     bf16x8 qr[NQ];
;     const bf16_t* Qw = Qb + (unsigned)((wid * 32 + r32) * ldq + hi * 8);
; #pragma unroll
;     for (int d0 = 0; d0 < NQ; ++d0) qr[d0] = *(const bf16x8*)(Qw + d0 * 16);
;     const int qpos = qpos0 + wid * 32 + r32;
;     if (MODE == 0) {
; #pragma unroll
;         for (int dd = 0; dd < 2; ++dd) rot8(qr[(MODE == 0) ? 8 + dd : 0], qr[(MODE == 0) ? 10 + dd : 1], TA + (unsigned)(qpos * 32 + dd * 16 + hi * 8));
;     } else if (MODE == 1) {
;         rot8(qr[0], qr[1], TB + (unsigned)(qpos * 16 + hi * 8));
;     } else {
;         float ss = 0.f;
; #pragma unroll
;         for (int d0 = 0; d0 < 8; ++d0) { float x[8]; unpack8(qr[d0], x);
; #pragma unroll
;             for (int j = 0; j < 8; ++j) ss += x[j] * x[j]; }
;         ss += __shfl_xor(ss, 32);
; template <int MODE>
; __device__ __forceinline__ void op_attn(const Ctx cx, const Params& p, LAS unsigned char* lds, int L, int sel) {
;     ...
;             const bf16_t* Kp = P + (size_t)row0 * BC_IN + 2048 + (h >> 2) * 128;
;             att::attn_unit<2>(cx, (LAS char*)lds, P + (size_t)(row0 + q0) * BC_IN + h * 128, BC_IN, Kp, Kp + 512, BC_IN,
;                               nullptr, P + (size_t)(row0 + q0) * BC_IN + BC_GATE + h * 128, BC_IN, seq, q0, 0, TA, TB, p.c_q_scale + j * 128, 0.f, dry);
.LBB0_250:
	s_mul_i32 s94, s5, 0x1400
	s_lshl_b32 s0, s0, 8
	s_lshl_b64 s[2:3], s[94:95], 1
	s_add_u32 s2, s58, s2
	s_addc_u32 s3, s59, s3
	s_lshl_b32 s6, s4, 6
	s_and_b32 s6, s6, 0xffffff00
	s_add_u32 s27, s2, s6
	v_mov_b32_e32 v68, v201
	s_addc_u32 s28, s3, 0
	s_add_u32 s8, s27, 0x1000
	v_ashrrev_i32_e32 v51, 4, v68
	v_and_b32_e32 v2, 0xfffff0, v51
	v_lshlrev_b32_e32 v3, 1, v51
	s_addc_u32 s9, s28, 0
	s_add_i32 s2, s0, s5
	v_lshlrev_b32_e32 v1, 3, v68
	v_and_or_b32 v2, v3, 8, v2
	s_mul_i32 s94, s2, 0x1400
	v_lshrrev_b32_e32 v2, 1, v2
	v_bfe_u32 v4, v1, 5, 2
	s_lshl_b64 s[2:3], s[94:95], 1
	v_and_b32_e32 v164, 0x78, v1
	v_or_b32_e32 v1, v2, v4
	s_add_u32 s21, s58, s2
	v_lshrrev_b32_e32 v3, 1, v51
	v_lshlrev_b32_e32 v53, 9, v1
	v_and_b32_e32 v1, 3, v51
	v_add_u32_e32 v50, 32, v51
	s_addc_u32 s22, s59, s3
	s_lshl_b32 s23, s4, 7
	s_lshl_b32 s2, s4, 8
	v_and_or_b32 v1, v3, 4, v1
	v_and_b32_e32 v2, 0xfffff0, v50
	v_lshlrev_b32_e32 v3, 1, v50
	s_add_u32 s2, s21, s2
	v_readfirstlane_b32 s26, v68
	v_and_or_b32 v2, v3, 8, v2
	s_addc_u32 s3, s22, 0
	s_ashr_i32 s20, s26, 6
	v_lshrrev_b32_e32 v2, 1, v2
	v_or_b32_e32 v2, v2, v4
	s_add_u32 s6, s27, 0xa1400
	v_lshlrev_b32_e32 v117, 9, v2
	v_mul_lo_u32 v2, v51, s74
	s_addc_u32 s7, s28, 0
	v_or_b32_e32 v180, v2, v164
	s_add_u32 s30, s27, 0xa1000
	v_and_b32_e32 v165, 31, v68
	v_add_u32_e32 v2, 0x28000, v180
	v_mov_b32_e32 v3, v181
	s_addc_u32 s31, s28, 0
	s_lshl_b32 s25, s20, 5
	v_bfe_u32 v166, v68, 5, 1
	v_lshlrev_b64 v[64:65], 1, v[180:181]
	v_lshlrev_b64 v[66:67], 1, v[2:3]
	s_waitcnt vmcnt(4)
	v_or_b32_e32 v34, s25, v165
	v_lshl_add_u64 v[4:5], s[8:9], 0, v[64:65]
	v_lshl_add_u64 v[2:3], s[8:9], 0, v[66:67]
	v_lshl_add_u64 v[10:11], s[6:7], 0, v[64:65]
	v_lshl_add_u64 v[14:15], s[30:31], 0, v[66:67]
	v_mul_lo_u32 v34, v34, s74
	v_lshlrev_b32_e32 v52, 3, v166
	v_mov_b32 v0, 0
	s_waitcnt lgkmcnt(0)
	global_load_dwordx4 v[26:29], v[4:5], off offset:1024
	global_load_dwordx4 v[30:33], v[2:3], off offset:1024
	global_load_dwordx4 v[6:9], v[4:5], off
	s_nop 0
	global_load_dwordx4 v[2:5], v[2:3], off
	v_or_b32_e32 v180, v34, v52
	global_load_dwordx4 v[18:21], v[10:11], off
	v_lshl_add_u64 v[34:35], v[180:181], 1, s[2:3]
	global_load_dwordx4 v[14:17], v[14:15], off
	v_lshl_add_u64 v[10:11], s[6:7], 0, v[66:67]
	global_load_dwordx4 v[22:25], v[10:11], off
	v_lshl_add_u64 v[10:11], s[30:31], 0, v[64:65]
	global_load_dwordx4 v[10:13], v[10:11], off
	s_nop 0
	global_load_dwordx4 v[56:59], v[34:35], off
	global_load_dwordx4 v[60:63], v[34:35], off offset:32
	global_load_dwordx4 v[70:73], v[34:35], off offset:64
	global_load_dwordx4 v[74:77], v[34:35], off offset:96
	global_load_dwordx4 v[46:49], v[34:35], off offset:128
	global_load_dwordx4 v[38:41], v[34:35], off offset:160
	global_load_dwordx4 v[42:45], v[34:35], off offset:192
	s_nop 0
	global_load_dwordx4 v[34:37], v[34:35], off offset:224
	v_lshlrev_b32_e32 v84, 6, v1
	v_lshlrev_b32_e32 v1, 1, v164
	v_and_b32_e32 v119, 48, v1
	v_or3_b32 v167, v53, v84, v119
	v_or3_b32 v168, v117, v84, v119
	v_and_b32_e32 v117, 32, v68
	v_or_b32_e32 v54, s0, v165
	s_movk_i32 s0, 0xffe0
	s_waitcnt vmcnt(7)
	v_and_b32_e32 v112, 0xffff0000, v56
	v_lshlrev_b32_e32 v118, 16, v56
	v_mul_f32_e32 v120, v112, v112
	v_lshlrev_b32_e32 v111, 16, v57
	v_fmac_f32_e32 v120, v118, v118
	v_and_b32_e32 v108, 0xffff0000, v57
	v_fmac_f32_e32 v120, v111, v111
	v_lshlrev_b32_e32 v107, 16, v58
	v_fmac_f32_e32 v120, v108, v108
	v_and_b32_e32 v105, 0xffff0000, v58
	v_fmac_f32_e32 v120, v107, v107
	v_lshlrev_b32_e32 v104, 16, v59
	v_fmac_f32_e32 v120, v105, v105
	v_and_b32_e32 v103, 0xffff0000, v59
	v_fmac_f32_e32 v120, v104, v104
	v_fmac_f32_e32 v120, v103, v103
	s_waitcnt vmcnt(6)
	v_lshlrev_b32_e32 v116, 16, v60
	v_and_b32_e32 v115, 0xffff0000, v60
	v_fmac_f32_e32 v120, v116, v116
	v_lshlrev_b32_e32 v114, 16, v61
	v_fmac_f32_e32 v120, v115, v115
	v_and_b32_e32 v113, 0xffff0000, v61
	v_fmac_f32_e32 v120, v114, v114
	v_lshlrev_b32_e32 v109, 16, v62
	v_fmac_f32_e32 v120, v113, v113
	v_and_b32_e32 v102, 0xffff0000, v62
	v_fmac_f32_e32 v120, v109, v109
	v_lshlrev_b32_e32 v57, 16, v63
	v_fmac_f32_e32 v120, v102, v102
	v_and_b32_e32 v53, 0xffff0000, v63
	v_fmac_f32_e32 v120, v57, v57
	v_fmac_f32_e32 v120, v53, v53
	s_waitcnt vmcnt(5)
	v_lshlrev_b32_e32 v110, 16, v70
	v_and_b32_e32 v100, 0xffff0000, v70
	v_fmac_f32_e32 v120, v110, v110
	v_lshlrev_b32_e32 v98, 16, v71
	v_fmac_f32_e32 v120, v100, v100
	v_and_b32_e32 v97, 0xffff0000, v71
	v_fmac_f32_e32 v120, v98, v98
	v_lshlrev_b32_e32 v95, 16, v72
	v_fmac_f32_e32 v120, v97, v97
	v_and_b32_e32 v94, 0xffff0000, v72
	v_fmac_f32_e32 v120, v95, v95
	v_lshlrev_b32_e32 v92, 16, v73
	v_fmac_f32_e32 v120, v94, v94
	v_and_b32_e32 v90, 0xffff0000, v73
	v_fmac_f32_e32 v120, v92, v92
	v_fmac_f32_e32 v120, v90, v90
	s_waitcnt vmcnt(4)
	v_lshlrev_b32_e32 v96, 16, v74
	v_and_b32_e32 v88, 0xffff0000, v74
	v_fmac_f32_e32 v120, v96, v96
	v_lshlrev_b32_e32 v86, 16, v75
	v_fmac_f32_e32 v120, v88, v88
	v_and_b32_e32 v83, 0xffff0000, v75
	v_fmac_f32_e32 v120, v86, v86
	v_lshlrev_b32_e32 v72, 16, v76
	v_fmac_f32_e32 v120, v83, v83
	v_and_b32_e32 v69, 0xffff0000, v76
	v_fmac_f32_e32 v120, v72, v72
	v_lshlrev_b32_e32 v61, 16, v77
	v_fmac_f32_e32 v120, v69, v69
	v_and_b32_e32 v56, 0xffff0000, v77
	v_fmac_f32_e32 v120, v61, v61
	v_fmac_f32_e32 v120, v56, v56
	s_waitcnt vmcnt(3)
	v_lshlrev_b32_e32 v81, 16, v46
	v_and_b32_e32 v79, 0xffff0000, v46
	v_fmac_f32_e32 v120, v81, v81
	v_lshlrev_b32_e32 v77, 16, v47
	v_fmac_f32_e32 v120, v79, v79
	v_and_b32_e32 v76, 0xffff0000, v47
	v_fmac_f32_e32 v120, v77, v77
	v_lshlrev_b32_e32 v71, 16, v48
	v_fmac_f32_e32 v120, v76, v76
	v_and_b32_e32 v63, 0xffff0000, v48
	v_fmac_f32_e32 v120, v71, v71
	v_lshlrev_b32_e32 v62, 16, v49
	v_fmac_f32_e32 v120, v63, v63
	v_and_b32_e32 v60, 0xffff0000, v49
	v_fmac_f32_e32 v120, v62, v62
	v_fmac_f32_e32 v120, v60, v60
	s_waitcnt vmcnt(2)
; template <int MODE> ...
;     ...
;         float ss = 0.f;
; #pragma unroll
;         for (int d0 = 0; d0 < 8; ++d0) { float x[8]; unpack8(qr[d0], x);
; #pragma unroll
;             for (int j = 0; j < 8; ++j) ss += x[j] * x[j]; }
;         ss += __shfl_xor(ss, 32);
;         const float rinv = 1.0f / sqrtf(ss * (1.0f / 128.0f) + EPS);
; #pragma unroll
;         for (int d0 = 0; d0 < 8; ++d0) { float x[8]; unpack8(qr[d0], x); const float* gs = qscale + d0 * 16 + hi * 8;
; #pragma unroll
;             for (int j = 0; j < 8; ++j) x[j] = x[j] * rinv * gs[j];
;             qr[d0] = pack8(x); }
	v_lshlrev_b32_e32 v73, 16, v38
	v_and_b32_e32 v59, 0xffff0000, v38
	v_fmac_f32_e32 v120, v73, v73
	v_lshlrev_b32_e32 v58, 16, v39
	v_fmac_f32_e32 v120, v59, v59
	v_and_b32_e32 v55, 0xffff0000, v39
	v_fmac_f32_e32 v120, v58, v58
	v_lshlrev_b32_e32 v47, 16, v40
	v_fmac_f32_e32 v120, v55, v55
	v_and_b32_e32 v46, 0xffff0000, v40
	v_fmac_f32_e32 v120, v47, v47
	v_lshlrev_b32_e32 v106, 16, v41
	v_fmac_f32_e32 v120, v46, v46
	v_and_b32_e32 v101, 0xffff0000, v41
	v_fmac_f32_e32 v120, v106, v106
	v_fmac_f32_e32 v120, v101, v101
	s_waitcnt vmcnt(1)
	v_lshlrev_b32_e32 v99, 16, v42
	v_and_b32_e32 v93, 0xffff0000, v42
	v_fmac_f32_e32 v120, v99, v99
	v_lshlrev_b32_e32 v91, 16, v43
	v_fmac_f32_e32 v120, v93, v93
	v_and_b32_e32 v89, 0xffff0000, v43
	v_fmac_f32_e32 v120, v91, v91
	v_lshlrev_b32_e32 v87, 16, v44
	v_fmac_f32_e32 v120, v89, v89
	v_and_b32_e32 v85, 0xffff0000, v44
	v_fmac_f32_e32 v120, v87, v87
	v_lshlrev_b32_e32 v82, 16, v45
	v_fmac_f32_e32 v120, v85, v85
	v_and_b32_e32 v80, 0xffff0000, v45
	v_fmac_f32_e32 v120, v82, v82
	v_fmac_f32_e32 v120, v80, v80
	s_waitcnt vmcnt(0)
	v_lshlrev_b32_e32 v78, 16, v34
	v_and_b32_e32 v75, 0xffff0000, v34
	v_fmac_f32_e32 v120, v78, v78
	v_lshlrev_b32_e32 v74, 16, v35
	v_fmac_f32_e32 v120, v75, v75
	v_and_b32_e32 v70, 0xffff0000, v35
	v_fmac_f32_e32 v120, v74, v74
	v_and_b32_e32 v43, 0xffff0000, v36
	v_lshlrev_b32_e32 v42, 16, v36
	v_fmac_f32_e32 v120, v70, v70
	v_pk_mul_f32 v[34:35], v[42:43], v[42:43]
	v_and_b32_e32 v45, 0xffff0000, v37
	v_add_f32_e32 v34, v34, v120
	v_lshlrev_b32_e32 v44, 16, v37
	v_add_f32_e32 v36, v35, v34
	v_pk_mul_f32 v[34:35], v[44:45], v[44:45]
	s_nop 0
	v_add_f32_e32 v34, v34, v36
	v_and_b32_e32 v36, 64, v190
	v_add_f32_e32 v34, v35, v34
	v_xor_b32_e32 v35, 32, v190
	v_add_u32_e32 v36, 64, v36
	v_cmp_lt_i32_e32 vcc, v35, v36
	s_nop 1
	v_cndmask_b32_e32 v35, v190, v35, vcc
	v_lshlrev_b32_e32 v35, 2, v35
	ds_bpermute_b32 v35, v35, v34
	s_waitcnt lgkmcnt(0)
	v_add_f32_e32 v34, v34, v35
	v_fmamk_f32 v34, v34, 0x3c000000, v186
	v_cmp_gt_f32_e32 vcc, s79, v34
	v_mul_f32_e32 v35, 0x4f800000, v34
	s_nop 0
	v_cndmask_b32_e32 v34, v34, v35, vcc
	v_sqrt_f32_e32 v35, v34
	s_nop 0
	v_add_u32_e32 v36, -1, v35
	v_fma_f32 v37, -v36, v35, v34
	v_cmp_ge_f32_e64 s[6:7], 0, v37
	v_add_u32_e32 v37, 1, v35
	s_nop 0
	v_cndmask_b32_e64 v36, v35, v36, s[6:7]
	v_fma_f32 v35, -v37, v35, v34
	v_cmp_lt_f32_e64 s[6:7], 0, v35
	s_nop 1
	v_cndmask_b32_e64 v35, v36, v37, s[6:7]
	v_mul_f32_e32 v36, 0x37800000, v35
	v_cndmask_b32_e32 v35, v35, v36, vcc
	v_cmp_class_f32_e32 vcc, v34, v187
	s_nop 1
	v_cndmask_b32_e32 v34, v35, v34, vcc
	v_div_scale_f32 v35, s[2:3], v34, v34, 1.0
	v_rcp_f32_e32 v36, v35
	s_add_i32 s2, 0, 0x10000
	v_fma_f32 v37, -v35, v36, 1.0
	v_fmac_f32_e32 v36, v37, v36
	v_div_scale_f32 v37, vcc, 1.0, v34, 1.0
	v_mul_f32_e32 v38, v37, v36
	v_fma_f32 v39, -v35, v38, v37
	v_fmac_f32_e32 v38, v39, v36
	v_fma_f32 v35, -v35, v38, v37
	v_div_fmas_f32 v35, v35, v36, v38
	v_div_fixup_f32 v84, v35, v34, 1.0
	global_load_dwordx4 v[34:37], v117, s[12:13] offset:16
	global_load_dwordx4 v[38:41], v117, s[12:13]
	v_mul_f32_e32 v48, v84, v118
	v_mul_f32_e32 v102, v84, v102
	v_mul_f32_e32 v57, v84, v57
	v_mul_f32_e32 v53, v84, v53
	v_mul_f32_e32 v92, v84, v92
	v_mul_f32_e32 v97, v84, v97
	v_mul_f32_e32 v95, v84, v95
	v_mul_f32_e32 v94, v84, v94
	v_mul_f32_e32 v100, v84, v100
	v_mul_f32_e32 v98, v84, v98
	v_mul_f32_e32 v72, v84, v72
	v_mul_f32_e32 v69, v84, v69
	v_mul_f32_e32 v61, v84, v61
	v_mul_f32_e32 v56, v84, v56
	v_mul_f32_e32 v88, v84, v88
	v_mul_f32_e32 v86, v84, v86
	v_mul_f32_e32 v83, v84, v83
	v_mul_f32_e32 v81, v84, v81
	v_mul_f32_e32 v79, v84, v79
	v_mul_f32_e32 v77, v84, v77
	v_mul_f32_e32 v76, v84, v76
	v_mul_f32_e32 v71, v84, v71
	v_mul_f32_e32 v63, v84, v63
	v_mul_f32_e32 v62, v84, v62
	v_mul_f32_e32 v60, v84, v60
	v_mul_f32_e32 v59, v84, v59
	v_mul_f32_e32 v58, v84, v58
	v_mul_f32_e32 v55, v84, v55
	v_mul_f32_e32 v46, v84, v46
	v_mul_f32_e32 v47, v84, v47
	v_mul_f32_e32 v80, v84, v80
	v_mul_f32_e32 v82, v84, v82
	v_mul_f32_e32 v42, v84, v42
	v_mul_f32_e32 v43, v84, v43
	v_mul_f32_e32 v44, v84, v44
	v_mul_f32_e32 v45, v84, v45
	s_waitcnt vmcnt(0)
	v_mul_f32_e32 v38, v38, v48
	v_mul_f32_e32 v48, v84, v112
	v_mul_f32_e32 v39, v39, v48
	v_mul_f32_e32 v48, v84, v111
	v_mul_f32_e32 v40, v40, v48
	v_mul_f32_e32 v48, v84, v108
	v_mul_f32_e32 v41, v41, v48
	v_mul_f32_e32 v48, v84, v107
	v_mul_f32_e32 v34, v34, v48
	v_mul_f32_e32 v48, v84, v105
	v_mul_f32_e32 v35, v35, v48
	v_mul_f32_e32 v48, v84, v104
	v_mul_f32_e32 v48, v36, v48
	v_mul_f32_e32 v36, v84, v103
	v_mul_f32_e32 v49, v37, v36
	v_cvt_pk_bf16_f32 v37, v38, v39
	v_cvt_pk_bf16_f32 v36, v40, v41
	v_cvt_pk_bf16_f32 v35, v34, v35
	v_cvt_pk_bf16_f32 v34, v48, v49
	global_load_dwordx4 v[38:41], v117, s[12:13] offset:80
	global_load_dwordx4 v[118:121], v117, s[12:13] offset:64
	v_mul_f32_e32 v48, v84, v116
	v_mul_f32_e32 v49, v84, v115
	v_mul_f32_e32 v103, v84, v114
	v_mul_f32_e32 v104, v84, v113
	v_mul_f32_e32 v105, v84, v109
	v_mul_f32_e32 v107, v84, v110
	s_waitcnt vmcnt(1)
	v_mul_f32_e32 v38, v38, v105
	s_waitcnt vmcnt(0)
	v_mul_f32_e32 v48, v118, v48
	v_mul_f32_e32 v49, v119, v49
	v_mul_f32_e32 v103, v120, v103
	v_mul_f32_e32 v104, v121, v104
	v_mul_f32_e32 v39, v39, v102
	v_mul_f32_e32 v40, v40, v57
	v_mul_f32_e32 v41, v41, v53
	v_cvt_pk_bf16_f32 v57, v48, v49
	v_cvt_pk_bf16_f32 v53, v103, v104
	v_cvt_pk_bf16_f32 v49, v38, v39
	v_cvt_pk_bf16_f32 v48, v40, v41
	global_load_dwordx4 v[38:41], v117, s[12:13] offset:144
	global_load_dwordx4 v[102:105], v117, s[12:13] offset:128
	s_waitcnt vmcnt(1)
	v_mul_f32_e32 v92, v40, v92
	v_mul_f32_e32 v40, v84, v90
	s_waitcnt vmcnt(0)
; __device__ __forceinline__ void rot8(bf16x8& a, bf16x8& b, const f32x2* t) {
;     float x1[8], x2[8], y1[8], y2[8]; unpack8(a, x1); unpack8(b, x2);
; #pragma unroll
;     for (int j = 0; j < 8; ++j) { const f32x2 cs = t[j]; y1[j] = x1[j] * cs.x - x2[j] * cs.y; y2[j] = x2[j] * cs.x + x1[j] * cs.y; }
;     a = pack8(y1); b = pack8(y2);
; }
; template <int MODE> ...
;     ...
;         for (int d0 = 0; d0 < 8; ++d0) { float x[8]; unpack8(qr[d0], x); const float* gs = qscale + d0 * 16 + hi * 8;
; #pragma unroll
;             for (int j = 0; j < 8; ++j) x[j] = x[j] * rinv * gs[j];
;             qr[d0] = pack8(x); }
;         const int pr = qpos >> 6, pc = qpos & 63;
; #pragma unroll
;         for (int dd = 0; dd < 2; ++dd) { rot8(qr[dd], qr[2 + dd], TA + (unsigned)(pr * 32 + dd * 16 + hi * 8)); rot8(qr[4 + dd], qr[6 + dd], TA + (unsigned)(pc * 32 + dd * 16 + hi * 8)); }
	v_mul_f32_e32 v102, v102, v107
	v_mul_f32_e32 v97, v105, v97
	v_mul_f32_e32 v38, v38, v95
	v_mul_f32_e32 v39, v39, v94
	v_mul_f32_e32 v90, v41, v40
	v_mul_f32_e32 v100, v103, v100
	v_mul_f32_e32 v98, v104, v98
	v_cvt_pk_bf16_f32 v41, v102, v100
	v_cvt_pk_bf16_f32 v40, v98, v97
	v_cvt_pk_bf16_f32 v39, v38, v39
	v_cvt_pk_bf16_f32 v38, v92, v90
	v_mul_f32_e32 v90, v84, v96
	global_load_dwordx4 v[94:97], v117, s[12:13] offset:208
	global_load_dwordx4 v[102:105], v117, s[12:13] offset:192
	s_waitcnt vmcnt(1)
	v_mul_f32_e32 v92, v94, v72
	v_mul_f32_e32 v94, v95, v69
	v_mul_f32_e32 v95, v96, v61
	v_mul_f32_e32 v56, v97, v56
	s_waitcnt vmcnt(0)
	v_mul_f32_e32 v90, v102, v90
	v_mul_f32_e32 v88, v103, v88
	v_mul_f32_e32 v86, v104, v86
	v_mul_f32_e32 v83, v105, v83
	v_cvt_pk_bf16_f32 v72, v90, v88
	v_cvt_pk_bf16_f32 v69, v86, v83
	v_cvt_pk_bf16_f32 v61, v92, v94
	v_cvt_pk_bf16_f32 v56, v95, v56
	global_load_dwordx4 v[94:97], v117, s[12:13] offset:272
	global_load_dwordx4 v[102:105], v117, s[12:13] offset:256
	s_waitcnt vmcnt(1)
	v_mul_f32_e32 v71, v94, v71
	s_waitcnt vmcnt(0)
	v_mul_f32_e32 v81, v102, v81
	v_mul_f32_e32 v79, v103, v79
	v_mul_f32_e32 v77, v104, v77
	v_mul_f32_e32 v76, v105, v76
	v_mul_f32_e32 v63, v95, v63
	v_mul_f32_e32 v62, v96, v62
	v_mul_f32_e32 v60, v97, v60
	v_cvt_pk_bf16_f32 v81, v81, v79
	v_cvt_pk_bf16_f32 v79, v77, v76
	v_cvt_pk_bf16_f32 v77, v71, v63
	v_cvt_pk_bf16_f32 v76, v62, v60
	global_load_dwordx4 v[94:97], v117, s[12:13] offset:336
	global_load_dwordx4 v[102:105], v117, s[12:13] offset:320
	v_mul_f32_e32 v60, v84, v73
	v_mul_f32_e32 v62, v84, v106
	v_mul_f32_e32 v63, v84, v101
	v_mul_f32_e32 v73, v84, v85
	v_mul_f32_e32 v71, v84, v87
	s_waitcnt vmcnt(1)
	v_mul_f32_e32 v46, v46, v95
	s_waitcnt vmcnt(0)
	v_mul_f32_e32 v60, v102, v60
	v_mul_f32_e32 v59, v103, v59
	v_mul_f32_e32 v58, v104, v58
	v_mul_f32_e32 v55, v105, v55
	v_mul_f32_e32 v47, v47, v94
	v_mul_f32_e32 v62, v62, v96
	v_mul_f32_e32 v63, v63, v97
	v_cvt_pk_bf16_f32 v60, v60, v59
	v_cvt_pk_bf16_f32 v59, v58, v55
	v_cvt_pk_bf16_f32 v58, v47, v46
	v_cvt_pk_bf16_f32 v55, v62, v63
	v_mul_f32_e32 v46, v84, v99
	global_load_dwordx4 v[94:97], v117, s[12:13] offset:400
	global_load_dwordx4 v[98:101], v117, s[12:13] offset:384
	v_mul_f32_e32 v47, v84, v93
	v_mul_f32_e32 v62, v84, v91
	v_mul_f32_e32 v63, v84, v89
	s_waitcnt vmcnt(1)
	v_mul_f32_e32 v73, v73, v95
	v_mul_f32_e32 v86, v80, v97
	s_waitcnt vmcnt(0)
	v_mul_f32_e32 v46, v46, v98
	v_mul_f32_e32 v47, v47, v99
	v_mul_f32_e32 v62, v62, v100
	v_mul_f32_e32 v63, v63, v101
	v_mul_f32_e32 v71, v71, v94
	v_mul_f32_e32 v85, v82, v96
	v_cvt_pk_bf16_f32 v83, v46, v47
	v_cvt_pk_bf16_f32 v82, v62, v63
	v_cvt_pk_bf16_f32 v80, v71, v73
	v_cvt_pk_bf16_f32 v73, v85, v86
	global_load_dwordx4 v[86:89], v117, s[12:13] offset:464
	global_load_dwordx4 v[90:93], v117, s[12:13] offset:448
	v_mul_f32_e32 v63, v84, v70
	v_mul_f32_e32 v46, v84, v78
	v_mul_f32_e32 v47, v84, v75
	v_mul_f32_e32 v62, v84, v74
	v_lshlrev_b32_e32 v75, 16, v37
	v_lshlrev_b32_e32 v74, 16, v41
	s_waitcnt vmcnt(1)
	v_mul_f32_e32 v42, v42, v86
	s_waitcnt vmcnt(0)
	v_mul_f32_e32 v63, v63, v93
	v_mul_f32_e32 v46, v46, v90
	v_mul_f32_e32 v47, v47, v91
	v_mul_f32_e32 v62, v62, v92
	v_mul_f32_e32 v43, v43, v87
	v_cvt_pk_bf16_f32 v71, v46, v47
	v_cvt_pk_bf16_f32 v70, v62, v63
	v_cvt_pk_bf16_f32 v63, v42, v43
	v_add_u32_e32 v42, s25, v54
	v_ashrrev_i32_e32 v43, 1, v42
	v_and_or_b32 v180, v43, s0, v52
	v_mul_f32_e32 v44, v44, v88
	v_mul_f32_e32 v45, v45, v89
	v_lshlrev_b32_e32 v42, 5, v42
	s_movk_i32 s0, 0x7e0
	v_lshl_add_u64 v[46:47], v[180:181], 3, s[80:81]
	v_cvt_pk_bf16_f32 v62, v44, v45
	v_and_or_b32 v52, v42, s0, v52
	global_load_dwordx4 v[42:45], v[46:47], off offset:48
	global_load_dwordx4 v[84:87], v[46:47], off offset:32
	global_load_dwordx4 v[88:91], v[46:47], off offset:16
	global_load_dwordx4 v[92:95], v[46:47], off
	v_lshlrev_b32_e32 v52, 3, v52
	s_lshl_b32 s0, s20, 2
	s_add_i32 s0, s0, 0
	s_add_i32 s0, s0, 0x22880
	s_waitcnt vmcnt(0)
	v_pk_mul_f32 v[96:97], v[92:93], v[74:75] op_sel:[0,1] op_sel_hi:[1,0]
	v_pk_mul_f32 v[74:75], v[92:93], v[74:75]
	v_sub_f32_e32 v54, v96, v97
	v_add_f32_e32 v78, v75, v74
	v_and_b32_e32 v75, 0xffff0000, v37
	v_and_b32_e32 v74, 0xffff0000, v41
	v_pk_mul_f32 v[92:93], v[94:95], v[74:75] op_sel:[0,1] op_sel_hi:[1,0]
	v_pk_mul_f32 v[74:75], v[94:95], v[74:75]
	v_and_b32_e32 v37, 0xffff0000, v36
	v_add_f32_e32 v94, v75, v74
	v_lshlrev_b32_e32 v75, 16, v36
	v_and_b32_e32 v36, 0xffff0000, v40
	v_lshlrev_b32_e32 v74, 16, v40
	v_pk_mul_f32 v[40:41], v[90:91], v[36:37] op_sel:[0,1] op_sel_hi:[1,0]
	v_pk_mul_f32 v[36:37], v[90:91], v[36:37]
	v_sub_f32_e32 v96, v92, v93
	v_pk_mul_f32 v[92:93], v[88:89], v[74:75] op_sel:[0,1] op_sel_hi:[1,0]
	v_pk_mul_f32 v[74:75], v[88:89], v[74:75]
	v_add_f32_e32 v88, v36, v37
	v_lshlrev_b32_e32 v37, 16, v35
	v_lshlrev_b32_e32 v36, 16, v39
	v_add_f32_e32 v74, v74, v75
	v_sub_f32_e32 v75, v40, v41
	v_pk_mul_f32 v[40:41], v[84:85], v[36:37] op_sel:[0,1] op_sel_hi:[1,0]
	v_pk_mul_f32 v[36:37], v[84:85], v[36:37]
	v_sub_f32_e32 v89, v40, v41
	v_add_f32_e32 v84, v36, v37
	v_and_b32_e32 v37, 0xffff0000, v35
	v_and_b32_e32 v36, 0xffff0000, v39
	v_pk_mul_f32 v[40:41], v[86:87], v[36:37] op_sel:[0,1] op_sel_hi:[1,0]
	v_pk_mul_f32 v[36:37], v[86:87], v[36:37]
	v_sub_f32_e32 v39, v40, v41
	v_add_f32_e32 v85, v36, v37
	v_lshlrev_b32_e32 v37, 16, v34
	v_lshlrev_b32_e32 v36, 16, v38
	v_pk_mul_f32 v[40:41], v[42:43], v[36:37] op_sel:[0,1] op_sel_hi:[1,0]
	v_pk_mul_f32 v[36:37], v[42:43], v[36:37]
	v_and_b32_e32 v35, 0xffff0000, v34
	v_and_b32_e32 v34, 0xffff0000, v38
	v_sub_f32_e32 v40, v40, v41
	v_add_f32_e32 v41, v36, v37
	v_pk_mul_f32 v[36:37], v[44:45], v[34:35] op_sel:[0,1] op_sel_hi:[1,0]
	v_pk_mul_f32 v[34:35], v[44:45], v[34:35]
	v_sub_f32_e32 v36, v36, v37
	v_add_f32_e32 v34, v34, v35
	v_sub_f32_e32 v92, v92, v93
	v_cvt_pk_bf16_f32 v96, v54, v96
	v_cvt_pk_bf16_f32 v97, v92, v75
	v_cvt_pk_bf16_f32 v98, v89, v39
	v_cvt_pk_bf16_f32 v99, v40, v36
	v_cvt_pk_bf16_f32 v100, v78, v94
	v_cvt_pk_bf16_f32 v101, v74, v88
	v_cvt_pk_bf16_f32 v102, v84, v85
	v_cvt_pk_bf16_f32 v103, v41, v34
	global_load_dwordx4 v[34:37], v52, s[80:81] offset:48
	global_load_dwordx4 v[38:41], v52, s[80:81] offset:32
	global_load_dwordx4 v[42:45], v52, s[80:81] offset:16
	global_load_dwordx4 v[84:87], v52, s[80:81]
	v_lshlrev_b32_e32 v75, 16, v81
	v_lshlrev_b32_e32 v74, 16, v83
	s_waitcnt vmcnt(0)
; __device__ __forceinline__ void rot8(bf16x8& a, bf16x8& b, const f32x2* t) {
;     float x1[8], x2[8], y1[8], y2[8]; unpack8(a, x1); unpack8(b, x2);
; #pragma unroll
;     for (int j = 0; j < 8; ++j) { const f32x2 cs = t[j]; y1[j] = x1[j] * cs.x - x2[j] * cs.y; y2[j] = x2[j] * cs.x + x1[j] * cs.y; }
;     a = pack8(y1); b = pack8(y2);
; }
; template <int MODE> ...
;     ...
;         for (int dd = 0; dd < 2; ++dd) { rot8(qr[dd], qr[2 + dd], TA + (unsigned)(pr * 32 + dd * 16 + hi * 8)); rot8(qr[4 + dd], qr[6 + dd], TA + (unsigned)(pc * 32 + dd * 16 + hi * 8)); }
	v_pk_mul_f32 v[88:89], v[84:85], v[74:75] op_sel:[0,1] op_sel_hi:[1,0]
	v_pk_mul_f32 v[74:75], v[84:85], v[74:75]
	v_sub_f32_e32 v54, v88, v89
	v_add_f32_e32 v78, v75, v74
	v_and_b32_e32 v75, 0xffff0000, v81
	v_and_b32_e32 v74, 0xffff0000, v83
	v_pk_mul_f32 v[84:85], v[86:87], v[74:75] op_sel:[0,1] op_sel_hi:[1,0]
	v_pk_mul_f32 v[74:75], v[86:87], v[74:75]
	v_sub_f32_e32 v81, v84, v85
	v_add_f32_e32 v83, v75, v74
	v_lshlrev_b32_e32 v75, 16, v79
	v_lshlrev_b32_e32 v74, 16, v82
	v_pk_mul_f32 v[84:85], v[42:43], v[74:75] op_sel:[0,1] op_sel_hi:[1,0]
	v_pk_mul_f32 v[42:43], v[42:43], v[74:75]
	v_sub_f32_e32 v84, v84, v85
	v_add_f32_e32 v85, v42, v43
	v_and_b32_e32 v43, 0xffff0000, v79
	v_and_b32_e32 v42, 0xffff0000, v82
	v_pk_mul_f32 v[74:75], v[44:45], v[42:43] op_sel:[0,1] op_sel_hi:[1,0]
	v_pk_mul_f32 v[42:43], v[44:45], v[42:43]
	v_sub_f32_e32 v74, v74, v75
	v_add_f32_e32 v75, v42, v43
	v_lshlrev_b32_e32 v43, 16, v77
	v_lshlrev_b32_e32 v42, 16, v80
	v_pk_mul_f32 v[44:45], v[38:39], v[42:43] op_sel:[0,1] op_sel_hi:[1,0]
	v_pk_mul_f32 v[38:39], v[38:39], v[42:43]
	v_sub_f32_e32 v44, v44, v45
	v_add_f32_e32 v45, v38, v39
	v_and_b32_e32 v39, 0xffff0000, v77
	v_and_b32_e32 v38, 0xffff0000, v80
	v_pk_mul_f32 v[42:43], v[40:41], v[38:39] op_sel:[0,1] op_sel_hi:[1,0]
	v_pk_mul_f32 v[38:39], v[40:41], v[38:39]
	v_sub_f32_e32 v42, v42, v43
	v_add_f32_e32 v43, v38, v39
	v_lshlrev_b32_e32 v39, 16, v76
	v_lshlrev_b32_e32 v38, 16, v73
	v_pk_mul_f32 v[40:41], v[34:35], v[38:39] op_sel:[0,1] op_sel_hi:[1,0]
	v_pk_mul_f32 v[34:35], v[34:35], v[38:39]
	v_sub_f32_e32 v40, v40, v41
	v_add_f32_e32 v41, v34, v35
	v_and_b32_e32 v35, 0xffff0000, v76
	v_and_b32_e32 v34, 0xffff0000, v73
	v_pk_mul_f32 v[38:39], v[36:37], v[34:35] op_sel:[0,1] op_sel_hi:[1,0]
	v_pk_mul_f32 v[34:35], v[36:37], v[34:35]
	v_sub_f32_e32 v38, v38, v39
	v_add_f32_e32 v34, v34, v35
	v_cvt_pk_bf16_f32 v104, v54, v81
	v_cvt_pk_bf16_f32 v105, v84, v74
	v_cvt_pk_bf16_f32 v106, v44, v42
	v_cvt_pk_bf16_f32 v107, v40, v38
	v_cvt_pk_bf16_f32 v108, v78, v83
	v_cvt_pk_bf16_f32 v109, v85, v75
	v_cvt_pk_bf16_f32 v110, v45, v43
	v_cvt_pk_bf16_f32 v111, v41, v34
	global_load_dwordx4 v[34:37], v[46:47], off offset:176
	global_load_dwordx4 v[38:41], v[46:47], off offset:160
	global_load_dwordx4 v[42:45], v[46:47], off offset:144
	global_load_dwordx4 v[74:77], v[46:47], off offset:128
	v_lshlrev_b32_e32 v47, 16, v57
	v_lshlrev_b32_e32 v46, 16, v72
	s_waitcnt vmcnt(0)
	v_pk_mul_f32 v[78:79], v[74:75], v[46:47] op_sel:[0,1] op_sel_hi:[1,0]
	v_pk_mul_f32 v[46:47], v[74:75], v[46:47]
	v_sub_f32_e32 v54, v78, v79
	v_add_f32_e32 v74, v47, v46
	v_and_b32_e32 v47, 0xffff0000, v57
	v_and_b32_e32 v46, 0xffff0000, v72
	v_pk_mul_f32 v[72:73], v[76:77], v[46:47] op_sel:[0,1] op_sel_hi:[1,0]
	v_pk_mul_f32 v[46:47], v[76:77], v[46:47]
	v_sub_f32_e32 v57, v72, v73
	v_add_f32_e32 v75, v47, v46
	v_lshlrev_b32_e32 v47, 16, v53
	v_lshlrev_b32_e32 v46, 16, v69
	v_pk_mul_f32 v[72:73], v[42:43], v[46:47] op_sel:[0,1] op_sel_hi:[1,0]
	v_pk_mul_f32 v[42:43], v[42:43], v[46:47]
	v_sub_f32_e32 v72, v72, v73
	v_add_f32_e32 v73, v42, v43
	v_and_b32_e32 v43, 0xffff0000, v53
	v_and_b32_e32 v42, 0xffff0000, v69
	v_pk_mul_f32 v[46:47], v[44:45], v[42:43] op_sel:[0,1] op_sel_hi:[1,0]
	v_pk_mul_f32 v[42:43], v[44:45], v[42:43]
	v_sub_f32_e32 v46, v46, v47
	v_add_f32_e32 v47, v42, v43
	v_lshlrev_b32_e32 v43, 16, v49
	v_lshlrev_b32_e32 v42, 16, v61
	v_pk_mul_f32 v[44:45], v[38:39], v[42:43] op_sel:[0,1] op_sel_hi:[1,0]
	v_pk_mul_f32 v[38:39], v[38:39], v[42:43]
	v_sub_f32_e32 v44, v44, v45
	v_add_f32_e32 v45, v38, v39
	v_and_b32_e32 v39, 0xffff0000, v49
	v_and_b32_e32 v38, 0xffff0000, v61
	v_pk_mul_f32 v[42:43], v[40:41], v[38:39] op_sel:[0,1] op_sel_hi:[1,0]
	v_pk_mul_f32 v[38:39], v[40:41], v[38:39]
	v_sub_f32_e32 v42, v42, v43
	v_add_f32_e32 v43, v38, v39
	v_lshlrev_b32_e32 v39, 16, v48
	v_lshlrev_b32_e32 v38, 16, v56
	v_pk_mul_f32 v[40:41], v[34:35], v[38:39] op_sel:[0,1] op_sel_hi:[1,0]
	v_pk_mul_f32 v[34:35], v[34:35], v[38:39]
	v_sub_f32_e32 v40, v40, v41
	v_add_f32_e32 v41, v34, v35
	v_and_b32_e32 v35, 0xffff0000, v48
	v_and_b32_e32 v34, 0xffff0000, v56
	v_pk_mul_f32 v[38:39], v[36:37], v[34:35] op_sel:[0,1] op_sel_hi:[1,0]
	v_pk_mul_f32 v[34:35], v[36:37], v[34:35]
	v_sub_f32_e32 v38, v38, v39
	v_add_f32_e32 v34, v34, v35
	v_cvt_pk_bf16_f32 v112, v54, v57
	v_cvt_pk_bf16_f32 v113, v72, v46
	v_cvt_pk_bf16_f32 v114, v44, v42
	v_cvt_pk_bf16_f32 v115, v40, v38
	v_cvt_pk_bf16_f32 v116, v74, v75
	v_cvt_pk_bf16_f32 v117, v73, v47
	v_cvt_pk_bf16_f32 v118, v45, v43
	v_cvt_pk_bf16_f32 v119, v41, v34
	global_load_dwordx4 v[34:37], v52, s[80:81] offset:176
	global_load_dwordx4 v[38:41], v52, s[80:81] offset:160
	global_load_dwordx4 v[42:45], v52, s[80:81] offset:144
	global_load_dwordx4 v[46:49], v52, s[80:81] offset:128
	v_lshlrev_b32_e32 v53, 16, v60
	v_lshlrev_b32_e32 v52, 16, v71
	v_add_u32_e32 v69, 0, v167
	s_waitcnt vmcnt(0)
; #define LAS __attribute__((address_space(3)))
; __device__ __forceinline__ int v_rd_base(int lane) { return ((lane & 3) << 3) | (((lane >> 2) & 3) << 6) | (((lane >> 4) & 1) << 5) | (((lane >> 5) & 1) << 8); }
; #define SLOAD(k0) SLOADX(sg, k0)
; template <int MODE> ...
;     ...
;         for (int dd = 0; dd < 2; ++dd) { rot8(qr[dd], qr[2 + dd], TA + (unsigned)(pr * 32 + dd * 16 + hi * 8)); rot8(qr[4 + dd], qr[6 + dd], TA + (unsigned)(pc * 32 + dd * 16 + hi * 8)); }
;     }
;     const int vb0 = (int)(uintptr_t)V_lds + v_rd_base(lane);
;     ...
;     const int qw = qpos0 + wid * 32;
;     ...
;     f32x16 p0, p1; float mn, al; bf16x8 pa0, pa1, pa2, pa3; const int NT = nkeys / 64;
;     const int grp = __builtin_amdgcn_readfirstlane((int)((volatile LAS unsigned*)(lds + LDS_MISC))[32 + wid]);
;     int kb_[4], krb_[4], ka[4], kra[4];
; #pragma unroll
;     for (int i = 0; i < 4; ++i) { kb_[i] = (int)(uintptr_t)K_lds + r32 * 256 + ((i * 32 + hi * 16) ^ ((r32 & 7) << 4)); krb_[i] = (int)(uintptr_t)KR_lds + r32 * 128 + ((i * 32 + hi * 16) ^ (((r32 >> 1) & 7) << 4)); }
;     ...
;     asm volatile("s_waitcnt vmcnt(0)" ::: "memory"); SWRITEX(sg, 0, 0); SWRITEX(sh, 1, 1); if (2 < NT) SLOAD(128);
;     __syncthreads();
;     if (grp == 1) __syncthreads();
	v_pk_mul_f32 v[56:57], v[46:47], v[52:53] op_sel:[0,1] op_sel_hi:[1,0]
	v_pk_mul_f32 v[46:47], v[46:47], v[52:53]
	v_sub_f32_e32 v54, v56, v57
	v_add_f32_e32 v56, v47, v46
	v_and_b32_e32 v47, 0xffff0000, v60
	v_and_b32_e32 v46, 0xffff0000, v71
	v_pk_mul_f32 v[52:53], v[48:49], v[46:47] op_sel:[0,1] op_sel_hi:[1,0]
	v_pk_mul_f32 v[46:47], v[48:49], v[46:47]
	v_sub_f32_e32 v52, v52, v53
	v_add_f32_e32 v53, v47, v46
	v_lshlrev_b32_e32 v47, 16, v59
	v_lshlrev_b32_e32 v46, 16, v70
	v_pk_mul_f32 v[48:49], v[42:43], v[46:47] op_sel:[0,1] op_sel_hi:[1,0]
	v_pk_mul_f32 v[42:43], v[42:43], v[46:47]
	v_sub_f32_e32 v48, v48, v49
	v_add_f32_e32 v49, v42, v43
	v_and_b32_e32 v43, 0xffff0000, v59
	v_and_b32_e32 v42, 0xffff0000, v70
	v_pk_mul_f32 v[46:47], v[44:45], v[42:43] op_sel:[0,1] op_sel_hi:[1,0]
	v_pk_mul_f32 v[42:43], v[44:45], v[42:43]
	v_sub_f32_e32 v46, v46, v47
	v_add_f32_e32 v47, v42, v43
	v_lshlrev_b32_e32 v43, 16, v58
	v_lshlrev_b32_e32 v42, 16, v63
	v_pk_mul_f32 v[44:45], v[38:39], v[42:43] op_sel:[0,1] op_sel_hi:[1,0]
	v_pk_mul_f32 v[38:39], v[38:39], v[42:43]
	v_sub_f32_e32 v44, v44, v45
	v_add_f32_e32 v45, v38, v39
	v_and_b32_e32 v39, 0xffff0000, v58
	v_and_b32_e32 v38, 0xffff0000, v63
	v_pk_mul_f32 v[42:43], v[40:41], v[38:39] op_sel:[0,1] op_sel_hi:[1,0]
	v_pk_mul_f32 v[38:39], v[40:41], v[38:39]
	v_sub_f32_e32 v42, v42, v43
	v_add_f32_e32 v43, v38, v39
	v_lshlrev_b32_e32 v39, 16, v55
	v_lshlrev_b32_e32 v38, 16, v62
	v_pk_mul_f32 v[40:41], v[34:35], v[38:39] op_sel:[0,1] op_sel_hi:[1,0]
	v_pk_mul_f32 v[34:35], v[34:35], v[38:39]
	v_sub_f32_e32 v40, v40, v41
	v_add_f32_e32 v41, v34, v35
	v_and_b32_e32 v35, 0xffff0000, v55
	v_and_b32_e32 v34, 0xffff0000, v62
	v_pk_mul_f32 v[38:39], v[36:37], v[34:35] op_sel:[0,1] op_sel_hi:[1,0]
	v_pk_mul_f32 v[34:35], v[36:37], v[34:35]
	v_sub_f32_e32 v38, v38, v39
	v_add_f32_e32 v34, v34, v35
	v_cvt_pk_bf16_f32 v120, v54, v52
	v_cvt_pk_bf16_f32 v121, v48, v46
	v_cvt_pk_bf16_f32 v122, v44, v42
	v_cvt_pk_bf16_f32 v123, v40, v38
	v_cvt_pk_bf16_f32 v124, v56, v53
	v_cvt_pk_bf16_f32 v125, v49, v47
	v_cvt_pk_bf16_f32 v126, v45, v43
	v_cvt_pk_bf16_f32 v127, v41, v34
	v_mov_b32_e32 v34, s0
	ds_read_b32 v34, v34
	s_waitcnt vmcnt(0)
	ds_write_b128 v69, v[26:29]
	v_lshlrev_b32_e32 v26, 8, v51
	v_and_b32_e32 v27, 0x70, v68
	v_bitop3_b32 v169, v1, v26, v27 bitop3:0xde
	v_add_u32_e32 v70, 0, v168
	v_add_u32_e32 v26, s2, v169
	ds_write_b128 v70, v[30:33]
	ds_write_b128 v26, v[6:9]
	v_lshlrev_b32_e32 v6, 8, v50
	s_add_i32 s0, 0, 0x14000
	v_bitop3_b32 v170, v1, v6, v27 bitop3:0xde
	s_add_u32 s6, s27, 0x141400
	v_add_u32_e32 v1, s2, v170
	s_addc_u32 s7, s28, 0
	ds_write_b128 v1, v[2:5]
	ds_write_b128 v69, v[18:21] offset:16384
	ds_write_b128 v70, v[22:25] offset:16384
	s_add_u32 s30, s27, 0x141000
	v_lshl_add_u64 v[2:3], s[6:7], 0, v[64:65]
	s_addc_u32 s31, s28, 0
	global_load_dwordx4 v[48:51], v[2:3], off
	v_lshl_add_u64 v[2:3], s[6:7], 0, v[66:67]
	global_load_dwordx4 v[56:59], v[2:3], off
	v_lshl_add_u64 v[2:3], s[30:31], 0, v[64:65]
	global_load_dwordx4 v[52:55], v[2:3], off
	v_lshl_add_u64 v[2:3], s[30:31], 0, v[66:67]
	global_load_dwordx4 v[60:63], v[2:3], off
	s_waitcnt lgkmcnt(6)
	v_readfirstlane_b32 s29, v34
	v_add_u32_e32 v1, s0, v169
	ds_write_b128 v1, v[10:13]
	v_add_u32_e32 v1, s0, v170
	s_cmp_lg_u32 s29, 1
	ds_write_b128 v1, v[14:17]
	s_waitcnt lgkmcnt(0)
	s_barrier
	s_cbranch_scc1 .LBB0_252
	s_barrier

; #define LAS __attribute__((address_space(3)))
; __device__ __forceinline__ int v_st(int k, int c) { const int kk = (k & ~0xC) | ((k & 4) << 1) | ((k & 8) >> 1); return ((kk >> 3) * 4 + (c >> 5)) * 512 + ((kk & 7) * 32 + (c & 31)) * 2; }
; #define SLOADX(S, k0) do { const bf16_t* Vt_ = Vh + (size_t)(k0) * ldk; const bf16_t* Kt_ = Kh + (size_t)(k0) * ldk; \
;     S.vs0 = *(const bf16x8*)(Vt_ + voff0); S.vs1 = *(const bf16x8*)(Vt_ + voff1); \
;     S.ks0 = *(const bf16x8*)(Kt_ + voff0); S.ks1 = *(const bf16x8*)(Kt_ + voff1); \
;     if (MODE == 0) S.kr = *(const bf16x8*)(KRh + (size_t)(k0) * 64 + kroff); } while (0)
; template <int MODE> ...
;     ...
;     const int sr = tid >> 4, sc = (tid & 15) * 8, vst0 = v_st(sr, sc), vst1 = v_st(32 + sr, sc);
;     const int krr = tid >> 3, krc = (tid & 7) * 8;
;     const unsigned voff0 = (unsigned)(sr * ldk + sc), voff1 = voff0 + 32u * (unsigned)ldk, kroff = (unsigned)(krr * 64 + krc);
;     struct Stg { bf16x8 vs0, vs1, ks0, ks1, kr; };
;     Stg sg, sh;
;     ...
;     SLOADX(sg, 0); SLOADX(sh, 64);
;     bf16x8 qr[NQ];
;     const bf16_t* Qw = Qb + (unsigned)((wid * 32 + r32) * ldq + hi * 8);
; #pragma unroll
;     for (int d0 = 0; d0 < NQ; ++d0) qr[d0] = *(const bf16x8*)(Qw + d0 * 16);
; template <int MODE>
; __device__ __forceinline__ void op_attn(const Ctx cx, const Params& p, LAS unsigned char* lds, int L, int sel) {
;     ...
;         if (MODE == 0) {
;             const bf16_t* Q = (const bf16_t*)(cx.ws + WS_Q); const bf16_t* KV = (const bf16_t*)(cx.ws + WS_KV); const bf16_t* KR = (const bf16_t*)(cx.ws + WS_KR);
;             const int lrow0 = row0 - sel * HALF_TOK;
;             const bool kx = (sel == 1) && (h < 4);
;             const bf16_t* Kb = kx ? (const bf16_t*)(cx.ws + WS_KVX) + (size_t)lrow0 * 1024 + h * 256 : KV + (size_t)lrow0 * 4096 + h * 256; const int ldkv = kx ? 1024 : 4096;
;             att::attn_unit<0>(cx, (LAS char*)lds, Q + (size_t)(lrow0 + q0) * 3072 + h * 192, 3072, Kb, Kb + 128, ldkv,
;                               KR + (size_t)row0 * 64, P + (size_t)(row0 + q0) * A_INP + A_GATE + h * 128, A_INP, seq, q0, 0, TA, TB, nullptr, 0.f, dry);
.LBB0_283:
	s_lshl_b32 s38, s0, 8
	s_sub_i32 s6, s2, s31
	s_cmp_lt_i32 s37, 4
	s_cselect_b64 s[4:5], -1, 0
	s_lshl_b32 s18, s37, 8
	s_and_b64 s[8:9], s[14:15], s[4:5]
	s_ashr_i32 s7, s6, 31
	s_ashr_i32 s19, s18, 31
	s_and_b64 s[4:5], s[8:9], exec
	s_mov_b32 s0, 0x13500000
	s_cselect_b32 s0, s0, 0xf000000
	s_add_u32 s0, s80, s0
	s_addc_u32 s3, s81, 0
	s_and_b64 s[4:5], s[8:9], exec
	s_cselect_b32 s5, 11, 13
	s_cselect_b32 s4, 0x400, s78
	s_lshl_b64 s[20:21], s[6:7], s5
	s_add_u32 s0, s0, s20
	s_addc_u32 s3, s3, s21
	s_lshl_b64 s[18:19], s[18:19], 1
	s_add_u32 s18, s0, s18
	s_addc_u32 s19, s3, s19
	s_add_i32 s0, s38, s6
	s_mul_hi_i32 s3, s0, 0x1800
	s_mulk_i32 s0, 0x1800
	s_add_u32 s0, s27, s0
	s_mul_i32 s6, s37, 0xc0
	s_addc_u32 s3, s28, s3
	s_ashr_i32 s7, s6, 31
	s_lshl_b64 s[6:7], s[6:7], 1
	s_add_u32 s22, s0, s6
	s_addc_u32 s23, s3, s7
	s_ashr_i32 s3, s2, 31
	v_mov_b32_e32 v76, v201
	s_lshl_b64 s[20:21], s[2:3], 7
	s_add_u32 s6, s29, s20
	v_ashrrev_i32_e32 v81, 4, v76
	v_readfirstlane_b32 s0, v76
	v_and_b32_e32 v1, 0xfffff0, v81
	v_lshlrev_b32_e32 v2, 1, v81
	s_addc_u32 s7, s30, s21
	s_ashr_i32 s3, s0, 6
	s_waitcnt lgkmcnt(0)
	v_lshlrev_b32_e32 v77, 3, v76
	v_and_or_b32 v1, v2, 8, v1
	v_lshrrev_b32_e32 v1, 1, v1
	v_bfe_u32 v3, v77, 5, 2
	s_and_b64 s[40:41], s[8:9], exec
	v_and_b32_e32 v202, 0x78, v77
	v_or_b32_e32 v1, v1, v3
	s_cselect_b32 s5, 10, 12
	v_lshrrev_b32_e32 v2, 1, v81
	v_lshlrev_b32_e32 v58, 9, v1
	v_and_b32_e32 v1, 3, v81
	v_lshl_or_b32 v180, v81, s5, v202
	s_lshl_b32 s5, s4, 7
	v_and_or_b32 v1, v2, 4, v1
	v_ashrrev_i32_e32 v79, 3, v76
	v_and_b32_e32 v80, 56, v77
	v_lshl_add_u32 v182, s4, 5, v180
	v_mov_b32_e32 v183, v181
	s_add_u32 s40, s18, s5
	v_lshlrev_b32_e32 v82, 6, v1
	v_lshlrev_b32_e32 v1, 1, v202
	v_add_u32_e32 v78, 32, v81
	s_waitcnt vmcnt(1)
	v_lshl_or_b32 v68, v79, 6, v80
	v_lshlrev_b64 v[72:73], 1, v[180:181]
	v_lshlrev_b64 v[70:71], 1, v[182:183]
	v_mov_b32_e32 v69, v181
	s_addc_u32 s41, s19, 0
	v_and_b32_e32 v203, 31, v76
	v_and_b32_e32 v2, 0xfffff0, v78
	v_lshlrev_b32_e32 v4, 1, v78
	s_waitcnt vmcnt(0)
	v_lshl_add_u64 v[66:67], v[68:69], 1, s[6:7]
	v_lshl_add_u64 v[14:15], s[40:41], 0, v[72:73]
	v_lshl_add_u64 v[16:17], s[40:41], 0, v[70:71]
	s_movk_i32 s5, 0x2000
	s_lshl_b32 s41, s3, 5
	v_and_b32_e32 v84, 48, v1
	v_bfe_u32 v204, v76, 5, 1
	v_and_or_b32 v2, v4, 8, v2
	v_add_co_u32_e32 v22, vcc, s5, v66
	v_or_b32_e32 v42, s41, v203
	s_movk_i32 s5, 0xc00
	v_or3_b32 v205, v58, v82, v84
	v_or_b32_e32 v58, s38, v203
	v_lshrrev_b32_e32 v2, 1, v2
	v_mul_lo_u32 v42, v42, s5
	v_lshlrev_b32_e32 v59, 3, v204
	v_add_u32_e32 v58, s41, v58
	v_or_b32_e32 v2, v2, v3
	v_or_b32_e32 v42, v42, v59
	v_mov_b32_e32 v43, v181
	v_lshl_or_b32 v58, v58, 5, v59
	v_mov_b32_e32 v59, v181
	v_lshlrev_b32_e32 v83, 9, v2
	v_lshl_add_u64 v[2:3], s[18:19], 0, v[72:73]
	v_lshl_add_u64 v[4:5], s[18:19], 0, v[70:71]
	v_addc_co_u32_e32 v23, vcc, 0, v67, vcc
	v_lshl_add_u64 v[46:47], v[42:43], 1, s[22:23]
	v_lshl_add_u64 v[74:75], v[58:59], 3, s[80:81]
	v_mov_b32 v0, 0
	global_load_dwordx4 v[26:29], v[2:3], off offset:256
	global_load_dwordx4 v[30:33], v[4:5], off offset:256
	global_load_dwordx4 v[10:13], v[2:3], off
	global_load_dwordx4 v[6:9], v[4:5], off
	global_load_dwordx4 v[34:37], v[14:15], off offset:256
	s_lshl_b32 s5, s3, 2
	global_load_dwordx4 v[2:5], v[66:67], off
	global_load_dwordx4 v[38:41], v[16:17], off offset:256
	global_load_dwordx4 v[18:21], v[14:15], off
	s_nop 0
	global_load_dwordx4 v[14:17], v[16:17], off
	s_add_i32 s5, s5, 0
	global_load_dwordx4 v[22:25], v[22:23], off
	s_nop 0
	global_load_dwordx4 v[96:99], v[46:47], off
	global_load_dwordx4 v[100:103], v[46:47], off offset:32
	global_load_dwordx4 v[104:107], v[46:47], off offset:64
	global_load_dwordx4 v[108:111], v[46:47], off offset:96
	global_load_dwordx4 v[112:115], v[46:47], off offset:128
	global_load_dwordx4 v[116:119], v[46:47], off offset:160
	global_load_dwordx4 v[120:123], v[46:47], off offset:192
	global_load_dwordx4 v[124:127], v[46:47], off offset:224
	global_load_dwordx4 v[50:53], v[46:47], off offset:256
	global_load_dwordx4 v[42:45], v[46:47], off offset:288
	global_load_dwordx4 v[54:57], v[46:47], off offset:320
	s_nop 0
	global_load_dwordx4 v[46:49], v[46:47], off offset:352
	s_nop 0
	global_load_dwordx4 v[58:61], v[74:75], off offset:48
	global_load_dwordx4 v[62:65], v[74:75], off offset:32
	global_load_dwordx4 v[86:89], v[74:75], off offset:16
	global_load_dwordx4 v[90:93], v[74:75], off
	s_add_i32 s5, s5, 0x22880
	v_or3_b32 v206, v83, v82, v84
	s_add_i32 s23, 0, 0x14000
	s_lshl_b32 s4, s4, 8
	s_waitcnt vmcnt(7)
	v_lshlrev_b32_e32 v95, 16, v50
	s_waitcnt vmcnt(5)
	v_lshlrev_b32_e32 v94, 16, v54
	s_waitcnt vmcnt(0)
; #define LAS __attribute__((address_space(3)))
; #define SLOAD(k0) SLOADX(sg, k0)
; __device__ __forceinline__ void rot8(bf16x8& a, bf16x8& b, const f32x2* t) {
;     float x1[8], x2[8], y1[8], y2[8]; unpack8(a, x1); unpack8(b, x2);
; #pragma unroll
;     for (int j = 0; j < 8; ++j) { const f32x2 cs = t[j]; y1[j] = x1[j] * cs.x - x2[j] * cs.y; y2[j] = x2[j] * cs.x + x1[j] * cs.y; }
;     a = pack8(y1); b = pack8(y2);
; }
; template <int MODE> ...
;     ...
;     const int qw = qpos0 + wid * 32;
;     ...
;     f32x16 p0, p1; float mn, al; bf16x8 pa0, pa1, pa2, pa3; const int NT = nkeys / 64;
;     const int grp = __builtin_amdgcn_readfirstlane((int)((volatile LAS unsigned*)(lds + LDS_MISC))[32 + wid]);
;     int kb_[4], krb_[4], ka[4], kra[4];
; #pragma unroll
;     for (int i = 0; i < 4; ++i) { kb_[i] = (int)(uintptr_t)K_lds + r32 * 256 + ((i * 32 + hi * 16) ^ ((r32 & 7) << 4)); krb_[i] = (int)(uintptr_t)KR_lds + r32 * 128 + ((i * 32 + hi * 16) ^ (((r32 >> 1) & 7) << 4)); }
;     ...
;     asm volatile("s_waitcnt vmcnt(0)" ::: "memory"); SWRITEX(sg, 0, 0); SWRITEX(sh, 1, 1); if (2 < NT) SLOAD(128);
;     __syncthreads();
;     if (grp == 1) __syncthreads();
	v_pk_mul_f32 v[128:129], v[90:91], v[94:95] op_sel:[0,1] op_sel_hi:[1,0]
	v_pk_mul_f32 v[90:91], v[90:91], v[94:95]
	v_sub_f32_e32 v85, v128, v129
	v_add_f32_e32 v132, v91, v90
	v_and_b32_e32 v91, 0xffff0000, v50
	v_and_b32_e32 v90, 0xffff0000, v54
	v_pk_mul_f32 v[94:95], v[92:93], v[90:91] op_sel:[0,1] op_sel_hi:[1,0]
	v_pk_mul_f32 v[90:91], v[92:93], v[90:91]
	v_sub_f32_e32 v94, v94, v95
	v_add_f32_e32 v95, v91, v90
	v_lshlrev_b32_e32 v91, 16, v51
	v_and_b32_e32 v51, 0xffff0000, v51
	v_and_b32_e32 v50, 0xffff0000, v55
	v_lshlrev_b32_e32 v90, 16, v55
	v_pk_mul_f32 v[54:55], v[88:89], v[50:51] op_sel:[0,1] op_sel_hi:[1,0]
	v_pk_mul_f32 v[50:51], v[88:89], v[50:51]
	v_pk_mul_f32 v[92:93], v[86:87], v[90:91] op_sel:[0,1] op_sel_hi:[1,0]
	v_pk_mul_f32 v[86:87], v[86:87], v[90:91]
	v_add_f32_e32 v88, v50, v51
	v_lshlrev_b32_e32 v51, 16, v52
	v_lshlrev_b32_e32 v50, 16, v56
	v_add_f32_e32 v86, v86, v87
	v_sub_f32_e32 v87, v54, v55
	v_pk_mul_f32 v[54:55], v[62:63], v[50:51] op_sel:[0,1] op_sel_hi:[1,0]
	v_pk_mul_f32 v[50:51], v[62:63], v[50:51]
	v_sub_f32_e32 v89, v54, v55
	v_add_f32_e32 v62, v50, v51
	v_and_b32_e32 v51, 0xffff0000, v52
	v_and_b32_e32 v50, 0xffff0000, v56
	v_pk_mul_f32 v[54:55], v[64:65], v[50:51] op_sel:[0,1] op_sel_hi:[1,0]
	v_pk_mul_f32 v[50:51], v[64:65], v[50:51]
	v_sub_f32_e32 v56, v54, v55
	v_add_f32_e32 v63, v50, v51
	v_lshlrev_b32_e32 v51, 16, v53
	v_lshlrev_b32_e32 v50, 16, v57
	v_pk_mul_f32 v[54:55], v[58:59], v[50:51] op_sel:[0,1] op_sel_hi:[1,0]
	v_pk_mul_f32 v[50:51], v[58:59], v[50:51]
	v_sub_f32_e32 v54, v54, v55
	v_add_f32_e32 v55, v50, v51
	v_and_b32_e32 v51, 0xffff0000, v53
	v_and_b32_e32 v50, 0xffff0000, v57
	v_pk_mul_f32 v[52:53], v[60:61], v[50:51] op_sel:[0,1] op_sel_hi:[1,0]
	v_pk_mul_f32 v[50:51], v[60:61], v[50:51]
	v_sub_f32_e32 v52, v52, v53
	v_add_f32_e32 v50, v50, v51
	v_sub_f32_e32 v92, v92, v93
	v_cvt_pk_bf16_f32 v128, v85, v94
	v_cvt_pk_bf16_f32 v129, v92, v87
	v_cvt_pk_bf16_f32 v130, v89, v56
	v_cvt_pk_bf16_f32 v131, v54, v52
	v_cvt_pk_bf16_f32 v132, v132, v95
	v_cvt_pk_bf16_f32 v133, v86, v88
	v_cvt_pk_bf16_f32 v134, v62, v63
	v_cvt_pk_bf16_f32 v135, v55, v50
	global_load_dwordx4 v[50:53], v[74:75], off offset:176
	global_load_dwordx4 v[54:57], v[74:75], off offset:160
	global_load_dwordx4 v[58:61], v[74:75], off offset:144
	global_load_dwordx4 v[62:65], v[74:75], off offset:128
	v_lshlrev_b32_e32 v75, 16, v42
	v_lshlrev_b32_e32 v74, 16, v46
	s_waitcnt vmcnt(0)
	v_pk_mul_f32 v[86:87], v[62:63], v[74:75] op_sel:[0,1] op_sel_hi:[1,0]
	v_pk_mul_f32 v[62:63], v[62:63], v[74:75]
	v_sub_f32_e32 v85, v86, v87
	v_add_f32_e32 v86, v63, v62
	v_and_b32_e32 v63, 0xffff0000, v42
	v_and_b32_e32 v62, 0xffff0000, v46
	v_pk_mul_f32 v[74:75], v[64:65], v[62:63] op_sel:[0,1] op_sel_hi:[1,0]
	v_pk_mul_f32 v[62:63], v[64:65], v[62:63]
	v_sub_f32_e32 v74, v74, v75
	v_add_f32_e32 v75, v63, v62
	v_lshlrev_b32_e32 v63, 16, v43
	v_and_b32_e32 v43, 0xffff0000, v43
	v_and_b32_e32 v42, 0xffff0000, v47
	v_lshlrev_b32_e32 v62, 16, v47
	v_pk_mul_f32 v[46:47], v[60:61], v[42:43] op_sel:[0,1] op_sel_hi:[1,0]
	v_pk_mul_f32 v[42:43], v[60:61], v[42:43]
	v_pk_mul_f32 v[64:65], v[58:59], v[62:63] op_sel:[0,1] op_sel_hi:[1,0]
	v_pk_mul_f32 v[58:59], v[58:59], v[62:63]
	v_add_f32_e32 v60, v42, v43
	v_lshlrev_b32_e32 v43, 16, v44
	v_lshlrev_b32_e32 v42, 16, v48
	v_add_f32_e32 v58, v58, v59
	v_sub_f32_e32 v59, v46, v47
	v_pk_mul_f32 v[46:47], v[54:55], v[42:43] op_sel:[0,1] op_sel_hi:[1,0]
	v_pk_mul_f32 v[42:43], v[54:55], v[42:43]
	v_sub_f32_e32 v61, v46, v47
	v_add_f32_e32 v54, v42, v43
	v_and_b32_e32 v43, 0xffff0000, v44
	v_and_b32_e32 v42, 0xffff0000, v48
	v_pk_mul_f32 v[46:47], v[56:57], v[42:43] op_sel:[0,1] op_sel_hi:[1,0]
	v_pk_mul_f32 v[42:43], v[56:57], v[42:43]
	v_sub_f32_e32 v48, v46, v47
	v_add_f32_e32 v55, v42, v43
	v_lshlrev_b32_e32 v43, 16, v45
	v_lshlrev_b32_e32 v42, 16, v49
	v_pk_mul_f32 v[46:47], v[50:51], v[42:43] op_sel:[0,1] op_sel_hi:[1,0]
	v_pk_mul_f32 v[42:43], v[50:51], v[42:43]
	v_sub_f32_e32 v46, v46, v47
	v_add_f32_e32 v47, v42, v43
	v_and_b32_e32 v43, 0xffff0000, v45
	v_and_b32_e32 v42, 0xffff0000, v49
	v_pk_mul_f32 v[44:45], v[52:53], v[42:43] op_sel:[0,1] op_sel_hi:[1,0]
	v_pk_mul_f32 v[42:43], v[52:53], v[42:43]
	v_sub_f32_e32 v64, v64, v65
	v_add_f32_e32 v42, v42, v43
	v_sub_f32_e32 v44, v44, v45
	v_cvt_pk_bf16_f32 v136, v85, v74
	v_cvt_pk_bf16_f32 v137, v64, v59
	v_cvt_pk_bf16_f32 v138, v61, v48
	v_cvt_pk_bf16_f32 v139, v46, v44
	v_cvt_pk_bf16_f32 v140, v86, v75
	v_cvt_pk_bf16_f32 v141, v58, v60
	v_cvt_pk_bf16_f32 v142, v54, v55
	v_cvt_pk_bf16_f32 v143, v47, v42
	v_mov_b32_e32 v42, s5
	v_add_u32_e32 v74, 0, v205
	ds_read_b32 v42, v42
	s_waitcnt vmcnt(0)
	ds_write_b128 v74, v[26:29]
	v_lshlrev_b32_e32 v26, 8, v81
	v_and_b32_e32 v27, 0x70, v76
	v_bitop3_b32 v207, v1, v26, v27 bitop3:0xde
	s_add_i32 s5, 0, 0x10000
	v_add_u32_e32 v75, 0, v206
	v_add_u32_e32 v26, s5, v207
	ds_write_b128 v75, v[30:33]
	ds_write_b128 v26, v[10:13]
	v_lshlrev_b32_e32 v10, 8, v78
	v_bitop3_b32 v208, v1, v10, v27 bitop3:0xde
	v_add_u32_e32 v1, s5, v208
	ds_write_b128 v1, v[6:9]
	v_lshlrev_b32_e32 v1, 7, v79
	v_lshlrev_b32_e32 v6, 1, v80
	v_bitop3_b32 v1, v6, v1, v27 bitop3:0xde
	v_add_u32_e32 v78, 0, v1
	v_add_u32_e32 v209, 0x1c000, v78
	v_add_u32_e32 v1, s23, v207
	ds_write_b128 v209, v[2:5]
	ds_write_b128 v74, v[34:37] offset:16384
	ds_write_b128 v75, v[38:41] offset:16384
	ds_write_b128 v1, v[18:21]
	v_add_u32_e32 v1, s23, v208
	s_add_u32 s42, s18, s4
	ds_write_b128 v1, v[14:17]
	v_add_u32_e32 v1, 0x1e000, v78
	s_addc_u32 s43, s19, 0
	ds_write_b128 v1, v[22:25]
	v_lshl_add_u64 v[2:3], s[42:43], 0, v[72:73]
	v_lshl_add_u64 v[4:5], s[42:43], 0, v[70:71]
	global_load_dwordx4 v[48:51], v[2:3], off offset:256
	global_load_dwordx4 v[60:63], v[4:5], off offset:256
	global_load_dwordx4 v[52:55], v[2:3], off
	global_load_dwordx4 v[56:59], v[4:5], off
	v_add_co_u32_e32 v2, vcc, 0x4000, v66
	s_waitcnt lgkmcnt(10)
	v_readfirstlane_b32 s22, v42
	v_addc_co_u32_e32 v3, vcc, 0, v67, vcc
	global_load_dwordx4 v[64:67], v[2:3], off
	s_cmp_lg_u32 s22, 1
	s_waitcnt lgkmcnt(0)
	s_barrier
	s_cbranch_scc1 .LBB0_285
	s_barrier
